# grid barrier: all workgroup leaders poll the global generation word directly (per-XCD relay word and its atomic removed)
# speedup vs baseline: 1.0073x; 1.0015x over previous
; DI unsigned xb_ld(unsigned* q) { return __hip_atomic_load(q, __ATOMIC_RELAXED, __HIP_MEMORY_SCOPE_AGENT); }
; DI unsigned xb_add(unsigned* q, unsigned v) { return __hip_atomic_fetch_add(q, v, __ATOMIC_RELAXED, __HIP_MEMORY_SCOPE_AGENT); }
; #define XB_SPIN(cond, bar) do { unsigned _sp = 0; while (cond) { __builtin_amdgcn_s_sleep(1); \
;     if ((++_sp & 255u) == 0u) { if (xb_ld(&(bar)[XB_TMO])) break; if (_sp > XB_SPIN_CAP) { atomicAdd(&(bar)[XB_TMO], 1u); break; } } } } while (0)
; DI void grid_bar(unsigned* bar, volatile LAS unsigned* st, int wid) {
;     ...
;             const unsigned old = xb_add(&bar[XB_XSUB(x)], 1u);
;             const unsigned gen = old / nloc;
;             if (old + 1u == (gen + 1u) * nloc) {
;                 __builtin_amdgcn_fence(__ATOMIC_RELEASE, "agent");
;                 asm volatile("s_waitcnt vmcnt(0)" ::: "memory");
;                 const unsigned og = xb_add(&bar[XB_TOP], 1u);
;                 const unsigned tg = og / nx;
;                 if (og + 1u == (tg + 1u) * nx) xb_add(&bar[XB_TOPGEN], 1u);
;                 else XB_SPIN(xb_ld(&bar[XB_TOPGEN]) == tg, bar);
;                 __builtin_amdgcn_fence(__ATOMIC_ACQUIRE, "agent");
;                 xb_add(&bar[XB_XGEN(x)], 1u);
;                 asm volatile("s_waitcnt vmcnt(0)" ::: "memory");
;             } else {
;                 XB_SPIN(xb_ld(&bar[XB_XGEN(x)]) == gen, bar);
.LBB0_261:
	s_or_b64 exec, exec, s[14:15]
	v_cvt_f32_u32_e32 v4, v2
	s_waitcnt vmcnt(0)
	v_readfirstlane_b32 s12, v3
	v_sub_u32_e32 v3, 0, v2
	v_rcp_iflag_f32_e32 v4, v4
	v_add_u32_e32 v5, s12, v1
	v_mul_f32_e32 v4, 0x4f7ffffe, v4
	v_cvt_u32_f32_e32 v4, v4
	v_mul_lo_u32 v1, v3, v4
	v_mul_hi_u32 v1, v4, v1
	v_add_u32_e32 v1, v4, v1
	v_mul_hi_u32 v1, v5, v1
	v_mul_lo_u32 v3, v1, v2
	v_sub_u32_e32 v3, v5, v3
	v_add_u32_e32 v4, 1, v1
	v_cmp_ge_u32_e32 vcc, v3, v2
	s_nop 1
	v_cndmask_b32_e32 v1, v1, v4, vcc
	v_sub_u32_e32 v4, v3, v2
	v_cndmask_b32_e32 v3, v3, v4, vcc
	v_add_u32_e32 v4, 1, v1
	v_cmp_ge_u32_e32 vcc, v3, v2
	v_add_u32_e32 v3, 1, v5
	s_nop 0
	v_cndmask_b32_e32 v1, v1, v4, vcc
	v_mul_lo_u32 v4, v2, v1
	v_add_u32_e32 v2, v4, v2
	v_cmp_ne_u32_e32 vcc, v3, v2
	s_and_saveexec_b64 s[12:13], vcc
	s_xor_b64 s[12:13], exec, s[12:13]
	s_cbranch_execz .LBB0_275
	s_waitcnt lgkmcnt(0)
	s_add_u32 s18, s8, 0xcd83500
	s_addc_u32 s19, s9, 0
	v_mov_b32_e32 v0, 0
	global_load_dword v0, v0, s[18:19] sc1
	s_waitcnt vmcnt(0)
	v_cmp_eq_u32_e32 vcc, v0, v1
	s_and_saveexec_b64 s[14:15], vcc
	s_cbranch_execz .LBB0_274
	s_add_u32 s16, s8, 0xcd80200
	s_addc_u32 s17, s9, 0
	s_mov_b32 s30, 1
	s_mov_b64 s[20:21], 0
	v_mov_b32_e32 v0, 0
	s_branch .LBB0_265

; DI unsigned xb_add(unsigned* q, unsigned v) { return __hip_atomic_fetch_add(q, v, __ATOMIC_RELAXED, __HIP_MEMORY_SCOPE_AGENT); }
; DI void grid_bar(unsigned* bar, volatile LAS unsigned* st, int wid) {
;     ...
;                 __builtin_amdgcn_fence(__ATOMIC_ACQUIRE, "agent");
;                 xb_add(&bar[XB_XGEN(x)], 1u);
;                 asm volatile("s_waitcnt vmcnt(0)" ::: "memory");
.LBB0_292:
	s_or_b64 exec, exec, s[8:9]
	s_mov_b64 s[8:9], exec
	v_mbcnt_lo_u32_b32 v0, s8, 0
	v_mbcnt_hi_u32_b32 v0, s9, v0
	v_cmp_eq_u32_e32 vcc, 0, v0
	s_waitcnt vmcnt(0)
	buffer_inv sc1
	s_and_saveexec_b64 s[12:13], vcc
	s_cbranch_execz .LBB0_294
	s_bcnt1_i32_b64 s8, s[8:9]
	v_mov_b32_e32 v0, 0x2000
	v_mov_b32_e32 v1, s8
.LBB0_294:
	s_or_b64 exec, exec, s[12:13]
	s_waitcnt vmcnt(0)

; DI unsigned xb_add(unsigned* q, unsigned v) { return __hip_atomic_fetch_add(q, v, __ATOMIC_RELAXED, __HIP_MEMORY_SCOPE_AGENT); }
; DI void grid_bar(unsigned* bar, volatile LAS unsigned* st, int wid) {
;     ...
;                 __builtin_amdgcn_fence(__ATOMIC_ACQUIRE, "agent");
;                 xb_add(&bar[XB_XGEN(x)], 1u);
;                 asm volatile("s_waitcnt vmcnt(0)" ::: "memory");
.LBB0_449:
	s_or_b64 exec, exec, s[8:9]
	s_mov_b64 s[8:9], exec
	v_mbcnt_lo_u32_b32 v0, s8, 0
	v_mbcnt_hi_u32_b32 v0, s9, v0
	v_cmp_eq_u32_e32 vcc, 0, v0
	s_waitcnt vmcnt(0)
	buffer_inv sc1
	s_and_saveexec_b64 s[12:13], vcc
	s_cbranch_execz .LBB0_451
	s_bcnt1_i32_b64 s8, s[8:9]
	v_mov_b32_e32 v0, 0x2000
	v_mov_b32_e32 v1, s8
.LBB0_451:
	s_or_b64 exec, exec, s[12:13]
	s_waitcnt vmcnt(0)

; DI unsigned xb_add(unsigned* q, unsigned v) { return __hip_atomic_fetch_add(q, v, __ATOMIC_RELAXED, __HIP_MEMORY_SCOPE_AGENT); }
; DI void grid_bar(unsigned* bar, volatile LAS unsigned* st, int wid) {
;     ...
;                 __builtin_amdgcn_fence(__ATOMIC_ACQUIRE, "agent");
;                 xb_add(&bar[XB_XGEN(x)], 1u);
;                 asm volatile("s_waitcnt vmcnt(0)" ::: "memory");
.LBB0_522:
	s_or_b64 exec, exec, s[8:9]
	s_mov_b64 s[8:9], exec
	v_mbcnt_lo_u32_b32 v0, s8, 0
	v_mbcnt_hi_u32_b32 v0, s9, v0
	v_cmp_eq_u32_e32 vcc, 0, v0
	s_waitcnt vmcnt(0)
	buffer_inv sc1
	s_and_saveexec_b64 s[12:13], vcc
	s_cbranch_execz .LBB0_524
	s_bcnt1_i32_b64 s8, s[8:9]
	v_mov_b32_e32 v0, 0x2000
	v_mov_b32_e32 v1, s8
.LBB0_524:
	s_or_b64 exec, exec, s[12:13]
	s_waitcnt vmcnt(0)

; DI unsigned xb_add(unsigned* q, unsigned v) { return __hip_atomic_fetch_add(q, v, __ATOMIC_RELAXED, __HIP_MEMORY_SCOPE_AGENT); }
; DI void grid_bar(unsigned* bar, volatile LAS unsigned* st, int wid) {
;     ...
;                 __builtin_amdgcn_fence(__ATOMIC_ACQUIRE, "agent");
;                 xb_add(&bar[XB_XGEN(x)], 1u);
;                 asm volatile("s_waitcnt vmcnt(0)" ::: "memory");
.LBB0_597:
	s_or_b64 exec, exec, s[8:9]
	s_mov_b64 s[8:9], exec
	v_mbcnt_lo_u32_b32 v0, s8, 0
	v_mbcnt_hi_u32_b32 v0, s9, v0
	v_cmp_eq_u32_e32 vcc, 0, v0
	s_waitcnt vmcnt(0)
	buffer_inv sc1
	s_and_saveexec_b64 s[12:13], vcc
	s_cbranch_execz .LBB0_599
	s_bcnt1_i32_b64 s8, s[8:9]
	v_mov_b32_e32 v0, 0x2000
	v_mov_b32_e32 v1, s8
.LBB0_599:
	s_or_b64 exec, exec, s[12:13]
	s_waitcnt vmcnt(0)

; DI unsigned xb_add(unsigned* q, unsigned v) { return __hip_atomic_fetch_add(q, v, __ATOMIC_RELAXED, __HIP_MEMORY_SCOPE_AGENT); }
; DI void grid_bar(unsigned* bar, volatile LAS unsigned* st, int wid) {
;     ...
;                 __builtin_amdgcn_fence(__ATOMIC_ACQUIRE, "agent");
;                 xb_add(&bar[XB_XGEN(x)], 1u);
;                 asm volatile("s_waitcnt vmcnt(0)" ::: "memory");
.LBB0_692:
	s_or_b64 exec, exec, s[8:9]
	s_mov_b64 s[8:9], exec
	v_mbcnt_lo_u32_b32 v0, s8, 0
	v_mbcnt_hi_u32_b32 v0, s9, v0
	v_cmp_eq_u32_e32 vcc, 0, v0
	s_waitcnt vmcnt(0)
	buffer_inv sc1
	s_and_saveexec_b64 s[12:13], vcc
	s_cbranch_execz .LBB0_694
	s_bcnt1_i32_b64 s8, s[8:9]
	v_mov_b32_e32 v0, 0x2000
	v_mov_b32_e32 v1, s8
.LBB0_694:
	s_or_b64 exec, exec, s[12:13]
	s_waitcnt vmcnt(0)

; DI unsigned xb_add(unsigned* q, unsigned v) { return __hip_atomic_fetch_add(q, v, __ATOMIC_RELAXED, __HIP_MEMORY_SCOPE_AGENT); }
; DI void grid_bar(unsigned* bar, volatile LAS unsigned* st, int wid) {
;     ...
;                 __builtin_amdgcn_fence(__ATOMIC_ACQUIRE, "agent");
;                 xb_add(&bar[XB_XGEN(x)], 1u);
;                 asm volatile("s_waitcnt vmcnt(0)" ::: "memory");
.LBB0_761:
	s_or_b64 exec, exec, s[8:9]
	s_mov_b64 s[8:9], exec
	v_mbcnt_lo_u32_b32 v0, s8, 0
	v_mbcnt_hi_u32_b32 v0, s9, v0
	v_cmp_eq_u32_e32 vcc, 0, v0
	s_waitcnt vmcnt(0)
	buffer_inv sc1
	s_and_saveexec_b64 s[12:13], vcc
	s_cbranch_execz .LBB0_763
	s_bcnt1_i32_b64 s8, s[8:9]
	v_mov_b32_e32 v0, 0x2000
	v_mov_b32_e32 v1, s8
.LBB0_763:
	s_or_b64 exec, exec, s[12:13]
	s_waitcnt vmcnt(0)

; DI unsigned xb_add(unsigned* q, unsigned v) { return __hip_atomic_fetch_add(q, v, __ATOMIC_RELAXED, __HIP_MEMORY_SCOPE_AGENT); }
; DI void grid_bar(unsigned* bar, volatile LAS unsigned* st, int wid) {
;     ...
;                 __builtin_amdgcn_fence(__ATOMIC_ACQUIRE, "agent");
;                 xb_add(&bar[XB_XGEN(x)], 1u);
;                 asm volatile("s_waitcnt vmcnt(0)" ::: "memory");
.LBB0_856:
	s_or_b64 exec, exec, s[8:9]
	s_mov_b64 s[8:9], exec
	v_mbcnt_lo_u32_b32 v0, s8, 0
	v_mbcnt_hi_u32_b32 v0, s9, v0
	v_cmp_eq_u32_e32 vcc, 0, v0
	s_waitcnt vmcnt(0)
	buffer_inv sc1
	s_and_saveexec_b64 s[12:13], vcc
	s_cbranch_execz .LBB0_858
	s_bcnt1_i32_b64 s8, s[8:9]
	v_mov_b32_e32 v0, 0x2000
	v_mov_b32_e32 v1, s8
.LBB0_858:
	s_or_b64 exec, exec, s[12:13]
	s_waitcnt vmcnt(0)

; DI unsigned xb_add(unsigned* q, unsigned v) { return __hip_atomic_fetch_add(q, v, __ATOMIC_RELAXED, __HIP_MEMORY_SCOPE_AGENT); }
; DI void grid_bar(unsigned* bar, volatile LAS unsigned* st, int wid) {
;     ...
;                 __builtin_amdgcn_fence(__ATOMIC_ACQUIRE, "agent");
;                 xb_add(&bar[XB_XGEN(x)], 1u);
;                 asm volatile("s_waitcnt vmcnt(0)" ::: "memory");
.LBB0_949:
	s_or_b64 exec, exec, s[8:9]
	s_mov_b64 s[8:9], exec
	v_mbcnt_lo_u32_b32 v0, s8, 0
	v_mbcnt_hi_u32_b32 v0, s9, v0
	v_cmp_eq_u32_e32 vcc, 0, v0
	s_waitcnt vmcnt(0)
	buffer_inv sc1
	s_and_saveexec_b64 s[12:13], vcc
	s_cbranch_execz .LBB0_951
	s_bcnt1_i32_b64 s8, s[8:9]
	v_mov_b32_e32 v0, 0x2000
	v_mov_b32_e32 v1, s8
.LBB0_951:
	s_or_b64 exec, exec, s[12:13]
	s_waitcnt vmcnt(0)

; DI unsigned xb_add(unsigned* q, unsigned v) { return __hip_atomic_fetch_add(q, v, __ATOMIC_RELAXED, __HIP_MEMORY_SCOPE_AGENT); }
; DI void grid_bar(unsigned* bar, volatile LAS unsigned* st, int wid) {
;     ...
;                 __builtin_amdgcn_fence(__ATOMIC_ACQUIRE, "agent");
;                 xb_add(&bar[XB_XGEN(x)], 1u);
;                 asm volatile("s_waitcnt vmcnt(0)" ::: "memory");
.LBB0_1068:
	s_or_b64 exec, exec, s[8:9]
	s_mov_b64 s[8:9], exec
	v_mbcnt_lo_u32_b32 v0, s8, 0
	v_mbcnt_hi_u32_b32 v0, s9, v0
	v_cmp_eq_u32_e32 vcc, 0, v0
	s_waitcnt vmcnt(0)
	buffer_inv sc1
	s_and_saveexec_b64 s[12:13], vcc
	s_cbranch_execz .LBB0_1070
	s_bcnt1_i32_b64 s8, s[8:9]
	v_mov_b32_e32 v0, 0x2000
	v_mov_b32_e32 v1, s8
.LBB0_1070:
	s_or_b64 exec, exec, s[12:13]
	s_waitcnt vmcnt(0)

; DI unsigned xb_add(unsigned* q, unsigned v) { return __hip_atomic_fetch_add(q, v, __ATOMIC_RELAXED, __HIP_MEMORY_SCOPE_AGENT); }
; DI void grid_bar(unsigned* bar, volatile LAS unsigned* st, int wid) {
;     ...
;                 __builtin_amdgcn_fence(__ATOMIC_ACQUIRE, "agent");
;                 xb_add(&bar[XB_XGEN(x)], 1u);
;                 asm volatile("s_waitcnt vmcnt(0)" ::: "memory");
.LBB0_1152:
	s_or_b64 exec, exec, s[8:9]
	s_mov_b64 s[8:9], exec
	v_mbcnt_lo_u32_b32 v0, s8, 0
	v_mbcnt_hi_u32_b32 v0, s9, v0
	v_cmp_eq_u32_e32 vcc, 0, v0
	s_waitcnt vmcnt(0)
	buffer_inv sc1
	s_and_saveexec_b64 s[12:13], vcc
	s_cbranch_execz .LBB0_1154
	s_bcnt1_i32_b64 s8, s[8:9]
	v_mov_b32_e32 v0, 0x2000
	v_mov_b32_e32 v1, s8
.LBB0_1154:
	s_or_b64 exec, exec, s[12:13]
	s_waitcnt vmcnt(0)

; DI unsigned xb_add(unsigned* q, unsigned v) { return __hip_atomic_fetch_add(q, v, __ATOMIC_RELAXED, __HIP_MEMORY_SCOPE_AGENT); }
; DI void grid_bar(unsigned* bar, volatile LAS unsigned* st, int wid) {
;     ...
;                 __builtin_amdgcn_fence(__ATOMIC_ACQUIRE, "agent");
;                 xb_add(&bar[XB_XGEN(x)], 1u);
;                 asm volatile("s_waitcnt vmcnt(0)" ::: "memory");
.LBB0_1247:
	s_or_b64 exec, exec, s[8:9]
	s_mov_b64 s[8:9], exec
	v_mbcnt_lo_u32_b32 v0, s8, 0
	v_mbcnt_hi_u32_b32 v0, s9, v0
	v_cmp_eq_u32_e32 vcc, 0, v0
	s_waitcnt vmcnt(0)
	buffer_inv sc1
	s_and_saveexec_b64 s[12:13], vcc
	s_cbranch_execz .LBB0_1249
	s_bcnt1_i32_b64 s8, s[8:9]
	v_mov_b32_e32 v0, 0x2000
	v_mov_b32_e32 v1, s8
.LBB0_1249:
	s_or_b64 exec, exec, s[12:13]
	s_waitcnt vmcnt(0)

; DI unsigned xb_add(unsigned* q, unsigned v) { return __hip_atomic_fetch_add(q, v, __ATOMIC_RELAXED, __HIP_MEMORY_SCOPE_AGENT); }
; DI void grid_bar(unsigned* bar, volatile LAS unsigned* st, int wid) {
;     ...
;                 __builtin_amdgcn_fence(__ATOMIC_ACQUIRE, "agent");
;                 xb_add(&bar[XB_XGEN(x)], 1u);
;                 asm volatile("s_waitcnt vmcnt(0)" ::: "memory");
.LBB0_1316:
	s_or_b64 exec, exec, s[8:9]
	s_mov_b64 s[8:9], exec
	v_mbcnt_lo_u32_b32 v0, s8, 0
	v_mbcnt_hi_u32_b32 v0, s9, v0
	v_cmp_eq_u32_e32 vcc, 0, v0
	s_waitcnt vmcnt(0)
	buffer_inv sc1
	s_and_saveexec_b64 s[12:13], vcc
	s_cbranch_execz .LBB0_1318
	s_bcnt1_i32_b64 s8, s[8:9]
	v_mov_b32_e32 v0, 0x2000
	v_mov_b32_e32 v1, s8
.LBB0_1318:
	s_or_b64 exec, exec, s[12:13]
	s_waitcnt vmcnt(0)

; DI unsigned xb_add(unsigned* q, unsigned v) { return __hip_atomic_fetch_add(q, v, __ATOMIC_RELAXED, __HIP_MEMORY_SCOPE_AGENT); }
; DI void grid_bar(unsigned* bar, volatile LAS unsigned* st, int wid) {
;     ...
;                 __builtin_amdgcn_fence(__ATOMIC_ACQUIRE, "agent");
;                 xb_add(&bar[XB_XGEN(x)], 1u);
;                 asm volatile("s_waitcnt vmcnt(0)" ::: "memory");
.LBB0_1411:
	s_or_b64 exec, exec, s[8:9]
	s_mov_b64 s[8:9], exec
	v_mbcnt_lo_u32_b32 v0, s8, 0
	v_mbcnt_hi_u32_b32 v0, s9, v0
	v_cmp_eq_u32_e32 vcc, 0, v0
	s_waitcnt vmcnt(0)
	buffer_inv sc1
	s_and_saveexec_b64 s[12:13], vcc
	s_cbranch_execz .LBB0_1413
	s_bcnt1_i32_b64 s8, s[8:9]
	v_mov_b32_e32 v0, 0x2000
	v_mov_b32_e32 v1, s8
.LBB0_1413:
	s_or_b64 exec, exec, s[12:13]
	s_waitcnt vmcnt(0)
